# cumulative log-forget scan: values loaded once and together (was 64 serialized loads with store waits)
# speedup vs baseline: 1.0087x; 1.0087x over previous
; __device__ __forceinline__ int tid_opaque() { int t = threadIdx.x; asm volatile("" : "+v"(t)); return t; }
; __global__ void __launch_bounds__(512, 2) mega(Params P, int ph_lo, int ph_hi) {
;     ...
;             for (int q = cs; q < 64; q += G) {
;                 if (tid_opaque() < 64) { const int lane = tid_opaque() & 63, b = q >> 2, h = q & 3; const long base = ((long)b * SEQ + 32 * lane) * 4 + h;
;                     float tot = 0.f;
;                     for (int i = 0; i < 32; ++i) tot += logf_[base + 4 * i];
;                     float inc = tot;
; #pragma unroll
;                     for (int o = 1; o < 64; o <<= 1) { const float t = __shfl_up(inc, o); if (lane >= o) inc += t; }
.LBB0_557:
	s_cmp_gt_i32 s2, 63
	s_cbranch_scc1 .LBB0_560
	v_mov_b32_e32 v0, v195
	s_nop 0
	v_cmp_gt_i32_e32 vcc, 64, v0
	s_and_saveexec_b64 s[0:1], vcc
	s_cbranch_execz .LBB0_556
	v_mov_b32_e32 v0, v195
	s_ashr_i32 s8, s2, 2
	s_ashr_i32 s9, s8, 31
	v_and_b32_e32 v0, 63, v0
	s_lshl_b64 s[8:9], s[8:9], 13
	v_lshl_or_b32 v2, v0, 7, s8
	v_and_or_b32 v2, s2, 3, v2
	v_mov_b32_e32 v3, s9
	v_lshlrev_b64 v[2:3], 2, v[2:3]
	v_lshl_add_u64 v[4:5], s[4:5], 0, v[2:3]
	s_waitcnt lgkmcnt(0)
	global_load_dword v6, v[4:5], off
	global_load_dword v149, v[4:5], off offset:16
	global_load_dword v150, v[4:5], off offset:32
	global_load_dword v151, v[4:5], off offset:48
	global_load_dword v152, v[4:5], off offset:64
	global_load_dword v153, v[4:5], off offset:80
	global_load_dword v154, v[4:5], off offset:96
	global_load_dword v155, v[4:5], off offset:112
	global_load_dword v156, v[4:5], off offset:128
	global_load_dword v157, v[4:5], off offset:144
	global_load_dword v158, v[4:5], off offset:160
	global_load_dword v159, v[4:5], off offset:176
	global_load_dword v160, v[4:5], off offset:192
	global_load_dword v161, v[4:5], off offset:208
	global_load_dword v162, v[4:5], off offset:224
	global_load_dword v163, v[4:5], off offset:240
	global_load_dword v164, v[4:5], off offset:256
	global_load_dword v165, v[4:5], off offset:272
	global_load_dword v166, v[4:5], off offset:288
	global_load_dword v167, v[4:5], off offset:304
	global_load_dword v168, v[4:5], off offset:320
	global_load_dword v169, v[4:5], off offset:336
	global_load_dword v170, v[4:5], off offset:352
	global_load_dword v171, v[4:5], off offset:368
	global_load_dword v172, v[4:5], off offset:384
	global_load_dword v173, v[4:5], off offset:400
	global_load_dword v174, v[4:5], off offset:416
	global_load_dword v175, v[4:5], off offset:432
	global_load_dword v176, v[4:5], off offset:448
	global_load_dword v177, v[4:5], off offset:464
	global_load_dword v178, v[4:5], off offset:480
	global_load_dword v179, v[4:5], off offset:496
	v_and_b32_e32 v5, 64, v248
	v_add_u32_e32 v8, -2, v248
	s_waitcnt vmcnt(0)
	v_add_f32_e32 v7, 0, v6
	v_add_f32_e32 v7, v7, v149
	v_add_f32_e32 v7, v7, v150
	v_add_f32_e32 v7, v7, v151
	v_add_f32_e32 v7, v7, v152
	v_add_f32_e32 v7, v7, v153
	v_add_f32_e32 v7, v7, v154
	v_add_f32_e32 v7, v7, v155
	v_add_f32_e32 v7, v7, v156
	v_add_f32_e32 v7, v7, v157
	v_add_f32_e32 v7, v7, v158
	v_add_f32_e32 v7, v7, v159
	v_add_f32_e32 v7, v7, v160
	v_add_f32_e32 v7, v7, v161
	v_add_f32_e32 v7, v7, v162
	v_add_f32_e32 v7, v7, v163
	v_add_f32_e32 v7, v7, v164
	v_add_f32_e32 v7, v7, v165
	v_add_f32_e32 v7, v7, v166
	v_add_f32_e32 v7, v7, v167
	v_add_f32_e32 v7, v7, v168
	v_add_f32_e32 v7, v7, v169
	v_add_f32_e32 v7, v7, v170
	v_add_f32_e32 v7, v7, v171
	v_add_f32_e32 v7, v7, v172
	v_add_f32_e32 v7, v7, v173
	v_add_f32_e32 v7, v7, v174
	v_add_f32_e32 v7, v7, v175
	v_add_f32_e32 v7, v7, v176
	v_add_f32_e32 v7, v7, v177
	v_add_f32_e32 v7, v7, v178
	v_add_f32_e32 v4, v7, v179
	v_add_u32_e32 v7, -1, v248
	v_cmp_lt_i32_e32 vcc, v7, v5
	s_nop 1
	v_cndmask_b32_e32 v7, v7, v248, vcc
	v_lshlrev_b32_e32 v7, 2, v7
	ds_bpermute_b32 v7, v7, v4
	v_cmp_eq_u32_e32 vcc, 0, v0
	s_waitcnt lgkmcnt(0)
	v_add_f32_e32 v7, v4, v7
	v_cndmask_b32_e32 v7, v7, v4, vcc
	v_cmp_lt_i32_e32 vcc, v8, v5
	s_nop 1
	v_cndmask_b32_e32 v8, v8, v248, vcc
	v_lshlrev_b32_e32 v8, 2, v8
	ds_bpermute_b32 v8, v8, v7
	v_cmp_gt_u32_e32 vcc, 2, v0
	s_waitcnt lgkmcnt(0)
	v_add_f32_e32 v8, v7, v8
	v_cndmask_b32_e32 v7, v8, v7, vcc
	v_add_u32_e32 v8, -4, v248
	v_cmp_lt_i32_e32 vcc, v8, v5
	s_nop 1
	v_cndmask_b32_e32 v8, v8, v248, vcc
	v_lshlrev_b32_e32 v8, 2, v8
	ds_bpermute_b32 v8, v8, v7
	v_cmp_gt_u32_e32 vcc, 4, v0
	s_waitcnt lgkmcnt(0)
	v_add_f32_e32 v8, v7, v8
	v_cndmask_b32_e32 v7, v8, v7, vcc
	v_add_u32_e32 v8, -8, v248
	v_cmp_lt_i32_e32 vcc, v8, v5
	s_nop 1
	v_cndmask_b32_e32 v8, v8, v248, vcc
	v_lshlrev_b32_e32 v8, 2, v8
	ds_bpermute_b32 v8, v8, v7
	v_cmp_gt_u32_e32 vcc, 8, v0
	s_waitcnt lgkmcnt(0)
; __global__ void __launch_bounds__(512, 2) mega(Params P, int ph_lo, int ph_hi) {
;     ...
;                     for (int o = 1; o < 64; o <<= 1) { const float t = __shfl_up(inc, o); if (lane >= o) inc += t; }
;                     float run = inc - tot;
;                     for (int i = 0; i < 32; ++i) { run += logf_[base + 4 * i]; cl[base + 4 * i] = run * LOG2E; } }
	v_add_f32_e32 v8, v7, v8
	v_cndmask_b32_e32 v7, v8, v7, vcc
	v_add_u32_e32 v8, -16, v248
	v_cmp_lt_i32_e32 vcc, v8, v5
	s_nop 1
	v_cndmask_b32_e32 v8, v8, v248, vcc
	v_lshlrev_b32_e32 v8, 2, v8
	ds_bpermute_b32 v8, v8, v7
	v_cmp_gt_u32_e32 vcc, 16, v0
	s_waitcnt lgkmcnt(0)
	v_add_f32_e32 v8, v7, v8
	v_cndmask_b32_e32 v7, v8, v7, vcc
	v_subrev_u32_e32 v8, 32, v248
	v_cmp_lt_i32_e32 vcc, v8, v5
	s_nop 1
	v_cndmask_b32_e32 v5, v8, v248, vcc
	v_lshlrev_b32_e32 v5, 2, v5
	ds_bpermute_b32 v5, v5, v7
	v_cmp_gt_u32_e32 vcc, 32, v0
	s_waitcnt lgkmcnt(0)
	v_add_f32_e32 v0, v7, v5
	v_cndmask_b32_e32 v0, v0, v7, vcc
	v_sub_f32_e32 v0, v0, v4
	v_lshl_add_u64 v[4:5], s[44:45], 0, v[2:3]
	v_add_f32_e32 v0, v0, v6
	v_mul_f32_e32 v6, 0x3fb8aa3b, v0
	global_store_dword v[4:5], v6, off
	v_add_f32_e32 v0, v0, v149
	v_mul_f32_e32 v6, 0x3fb8aa3b, v0
	global_store_dword v[4:5], v6, off offset:16
	v_add_f32_e32 v0, v0, v150
	v_mul_f32_e32 v6, 0x3fb8aa3b, v0
	global_store_dword v[4:5], v6, off offset:32
	v_add_f32_e32 v0, v0, v151
	v_mul_f32_e32 v6, 0x3fb8aa3b, v0
	global_store_dword v[4:5], v6, off offset:48
	v_add_f32_e32 v0, v0, v152
	v_mul_f32_e32 v6, 0x3fb8aa3b, v0
	global_store_dword v[4:5], v6, off offset:64
	v_add_f32_e32 v0, v0, v153
	v_mul_f32_e32 v6, 0x3fb8aa3b, v0
	global_store_dword v[4:5], v6, off offset:80
	v_add_f32_e32 v0, v0, v154
	v_mul_f32_e32 v6, 0x3fb8aa3b, v0
	global_store_dword v[4:5], v6, off offset:96
	v_add_f32_e32 v0, v0, v155
	v_mul_f32_e32 v6, 0x3fb8aa3b, v0
	global_store_dword v[4:5], v6, off offset:112
	v_add_f32_e32 v0, v0, v156
	v_mul_f32_e32 v6, 0x3fb8aa3b, v0
	global_store_dword v[4:5], v6, off offset:128
	v_add_f32_e32 v0, v0, v157
	v_mul_f32_e32 v6, 0x3fb8aa3b, v0
	global_store_dword v[4:5], v6, off offset:144
	v_add_f32_e32 v0, v0, v158
	v_mul_f32_e32 v6, 0x3fb8aa3b, v0
	global_store_dword v[4:5], v6, off offset:160
	v_add_f32_e32 v0, v0, v159
	v_mul_f32_e32 v6, 0x3fb8aa3b, v0
	global_store_dword v[4:5], v6, off offset:176
	v_add_f32_e32 v0, v0, v160
	v_mul_f32_e32 v6, 0x3fb8aa3b, v0
	global_store_dword v[4:5], v6, off offset:192
	v_add_f32_e32 v0, v0, v161
	v_mul_f32_e32 v6, 0x3fb8aa3b, v0
	global_store_dword v[4:5], v6, off offset:208
	v_add_f32_e32 v0, v0, v162
	v_mul_f32_e32 v6, 0x3fb8aa3b, v0
	global_store_dword v[4:5], v6, off offset:224
	v_add_f32_e32 v0, v0, v163
	v_mul_f32_e32 v6, 0x3fb8aa3b, v0
	global_store_dword v[4:5], v6, off offset:240
	v_add_f32_e32 v0, v0, v164
	v_mul_f32_e32 v6, 0x3fb8aa3b, v0
	global_store_dword v[4:5], v6, off offset:256
	v_add_f32_e32 v0, v0, v165
	v_mul_f32_e32 v6, 0x3fb8aa3b, v0
	global_store_dword v[4:5], v6, off offset:272
	v_add_f32_e32 v0, v0, v166
	v_mul_f32_e32 v6, 0x3fb8aa3b, v0
	global_store_dword v[4:5], v6, off offset:288
	v_add_f32_e32 v0, v0, v167
	v_mul_f32_e32 v6, 0x3fb8aa3b, v0
	global_store_dword v[4:5], v6, off offset:304
	v_add_f32_e32 v0, v0, v168
	v_mul_f32_e32 v6, 0x3fb8aa3b, v0
	global_store_dword v[4:5], v6, off offset:320
	v_add_f32_e32 v0, v0, v169
	v_mul_f32_e32 v6, 0x3fb8aa3b, v0
	global_store_dword v[4:5], v6, off offset:336
	v_add_f32_e32 v0, v0, v170
	v_mul_f32_e32 v6, 0x3fb8aa3b, v0
	global_store_dword v[4:5], v6, off offset:352
	v_add_f32_e32 v0, v0, v171
	v_mul_f32_e32 v6, 0x3fb8aa3b, v0
	global_store_dword v[4:5], v6, off offset:368
	v_add_f32_e32 v0, v0, v172
	v_mul_f32_e32 v6, 0x3fb8aa3b, v0
	global_store_dword v[4:5], v6, off offset:384
	v_add_f32_e32 v0, v0, v173
	v_mul_f32_e32 v6, 0x3fb8aa3b, v0
	global_store_dword v[4:5], v6, off offset:400
	v_add_f32_e32 v0, v0, v174
	v_mul_f32_e32 v6, 0x3fb8aa3b, v0
	global_store_dword v[4:5], v6, off offset:416
	v_add_f32_e32 v0, v0, v175
	v_mul_f32_e32 v6, 0x3fb8aa3b, v0
	global_store_dword v[4:5], v6, off offset:432
	v_add_f32_e32 v0, v0, v176
	v_mul_f32_e32 v6, 0x3fb8aa3b, v0
	global_store_dword v[4:5], v6, off offset:448
	v_add_f32_e32 v0, v0, v177
	v_mul_f32_e32 v6, 0x3fb8aa3b, v0
	global_store_dword v[4:5], v6, off offset:464
	v_add_f32_e32 v0, v0, v178
	v_mul_f32_e32 v6, 0x3fb8aa3b, v0
	global_store_dword v[4:5], v6, off offset:480
	v_add_f32_e32 v0, v0, v179
	v_mul_f32_e32 v6, 0x3fb8aa3b, v0
	global_store_dword v[4:5], v6, off offset:496
	s_branch .LBB0_556
